# segment-transition pass: the wave owning the serial section stays at s_setprio 1 outside it
# speedup vs baseline: 1.0354x; 1.0002x over previous
.LBB0_1034:
	s_or_b64 exec, exec, s[36:37]
	s_cmp_lg_u64 s[30:31], 0
	s_cbranch_scc1 .Le23_skip_a
	v_and_b32_e32 v33, 15, v113
	v_lshrrev_b32_e32 v35, 4, v113
	v_mul_u32_u24_e32 v36, 0x84, v35
	v_mul_u32_u24_e32 v37, 0x44, v33
	v_mul_u32_u24_e32 v38, 0x110, v35
	v_lshl_add_u32 v36, v33, 2, v36
	v_lshl_add_u32 v37, v35, 2, v37
	v_lshl_add_u32 v38, v33, 2, v38
	ds_read_b32 v40, v36 offset:8384
	ds_read_b32 v44, v37 offset:12544
	ds_read_b32 v41, v36 offset:8912
	ds_read_b32 v45, v37 offset:12560
	ds_read_b32 v42, v36 offset:9440
	ds_read_b32 v46, v37 offset:12576
	ds_read_b32 v43, v36 offset:9968
	ds_read_b32 v47, v37 offset:12592
	ds_read_b32 v214, v38 offset:13632
	ds_read_b32 v215, v38 offset:13700
	ds_read_b32 v216, v38 offset:13768
	ds_read_b32 v217, v38 offset:13836
	v_mul_u32_u24_e32 v88, 0x50, v33
	v_lshl_add_u32 v88, v35, 3, v88
	v_lshrrev_b32_e32 v39, 2, v113
	v_mul_u32_u24_e32 v39, 0x50, v39
	v_and_b32_e32 v33, 3, v113
	v_lshl_add_u32 v39, v33, 3, v39
	v_mov_b32_e32 v230, 0
	v_mov_b32_e32 v231, 0
	ds_write_b64 v39, v[230:231] offset:58336
	s_waitcnt lgkmcnt(11)
	v_mfma_f32_16x16x4_f32 v[220:223], v40, v44, 0
	s_waitcnt lgkmcnt(9)
	v_mfma_f32_16x16x4_f32 v[220:223], v41, v45, v[220:223]
	s_waitcnt lgkmcnt(7)
	v_mfma_f32_16x16x4_f32 v[220:223], v42, v46, v[220:223]
	s_waitcnt lgkmcnt(5)
	v_mfma_f32_16x16x4_f32 v[220:223], v43, v47, v[220:223]
	s_waitcnt lgkmcnt(1)
	s_nop 9
	v_mfma_f32_16x16x4_f32 v[224:227], v220, v214, 0
	v_mfma_f32_16x16x4_f32 v[224:227], v221, v215, v[224:227]
	v_mfma_f32_16x16x4_f32 v[224:227], v222, v216, v[224:227]
	v_mfma_f32_16x16x4_f32 v[224:227], v223, v217, v[224:227]
	s_nop 9
	v_cvt_pk_bf16_f32 v228, v224, v225
	v_cvt_pk_bf16_f32 v229, v226, v227
	ds_write_b64 v88, v[228:229] offset:59584
	s_setprio 1
